# static priority raise for the producer role: s_setprio 1 for the V-path waves 0-3 across the GDN chain step loop (they produce Vn for every wave), reset at phase 4 entry
# speedup vs baseline: 1.0036x; 1.0036x over previous
.LBB0_1019:
	s_and_b32 s12, s59, 4
	s_lshl_b32 s49, s12, 11
	s_lshl_b32 s12, s2, 1
	s_and_b32 s69, s12, 0x300
	s_lshl_b32 s12, s60, 3
	s_and_b32 s70, s12, 0xc0
	s_add_u32 s50, s6, s50
	s_addc_u32 s51, s7, s51
	v_lshlrev_b32_e32 v122, 1, v122
	v_or_b32_e32 v142, s68, v56
	v_lshl_add_u64 v[32:33], s[50:51], 0, v[122:123]
	v_mov_b32_e32 v133, v123
	v_ashrrev_i32_e32 v143, 31, v142
	v_lshl_add_u64 v[44:45], v[32:33], 0, v[132:133]
	v_lshl_add_u64 v[56:57], v[142:143], 1, s[6:7]
	global_load_dwordx4 v[32:35], v[44:45], off
	global_load_dwordx4 v[36:39], v[44:45], off offset:64
	global_load_dwordx4 v[40:43], v[44:45], off offset:128
	s_nop 0
	global_load_dwordx4 v[44:47], v[44:45], off offset:192
	s_nop 0
	global_load_dwordx4 v[48:51], v[52:53], off
	s_lshl_b32 s12, s48, 1
	v_lshl_add_u64 v[56:57], v[56:57], 0, v[132:133]
	s_lshl_b64 s[4:5], s[4:5], 2
	v_lshl_add_u64 v[60:61], v[56:57], 0, s[20:21]
	v_add_co_u32_e32 v56, vcc, s56, v56
	s_add_u32 s4, s65, s4
	v_lshl_add_u64 v[52:53], v[52:53], 0, s[12:13]
	v_addc_co_u32_e32 v57, vcc, 0, v57, vcc
	s_addc_u32 s5, s66, s5
	global_load_dwordx4 v[52:55], v[52:53], off
	s_nop 0
	global_load_dwordx4 v[56:59], v[56:57], off
	s_nop 0
	global_load_dwordx4 v[60:63], v[60:61], off offset:64
	v_lshl_add_u32 v129, v64, 4, 0
	global_load_dword v144, v123, s[4:5]
	s_lshl_b32 s4, s52, 11
	s_and_b32 s4, s4, 0xffffc000
	s_or_b32 s4, s4, s49
	s_ashr_i32 s5, s4, 31
	s_lshl_b64 s[4:5], s[4:5], 10
	s_bfe_u32 s6, s53, 0x20006
	v_sub_u32_e32 v65, v129, v65
	s_or_b32 s4, s4, s69
	v_lshlrev_b32_e32 v64, 12, v64
	v_lshl_add_u32 v131, s6, 5, v65
	v_add_u32_e32 v66, s67, v65
	s_or_b32 s4, s4, s70
	v_lshl_or_b32 v64, s6, 14, v64
	v_lshlrev_b32_e32 v65, 1, v125
	v_or3_b32 v64, s4, v64, v65
	v_mov_b32_e32 v65, s5
	s_waitcnt lgkmcnt(0)
	s_barrier
	v_lshl_add_u64 v[64:65], s[10:11], 0, v[64:65]
	v_lshl_add_u64 v[146:147], v[64:65], 0, s[22:23]
	v_mov_b32_e32 v64, 0
	s_mov_b32 s39, 0
	v_mul_u32_u24_e32 v141, 0x90, v125
	s_or_b32 s67, s38, 3
	s_or_b32 s68, s38, 4
	v_add_u32_e32 v145, v66, v127
	v_mov_b32_e32 v65, v64
	v_mov_b32_e32 v66, v64
	v_mov_b32_e32 v67, v64
	v_mov_b32_e32 v76, v64
	v_mov_b32_e32 v77, v64
	v_mov_b32_e32 v78, v64
	v_mov_b32_e32 v79, v64
	v_readfirstlane_b32 s98, v180
	s_lshr_b32 s98, s98, 6
	s_cmp_lt_u32 s98, 4
	s_cbranch_scc0 .Lchain_prio_skip
	s_setprio 1
